# P3 units, scan (b,h) and a/b units class-aligned; P2-P3 barrier keeps the device-wide arrival but drops the L2 writeback when the class sits on one XCC
# speedup vs baseline: 1.0151x; 1.0097x over previous
_Z10fwd_kernel6Params:
	s_load_dwordx8 s[4:11], s[0:1], 0x80
	s_load_dwordx4 s[92:95], s[0:1], 0xa0
	s_load_dword s3, s[0:1], 0xb0
	v_and_b32_e32 v211, 0x3ff, v0
	s_mov_b32 s74, s2
	v_cmp_gt_u32_e32 vcc, 2, v211
	s_waitcnt lgkmcnt(0)
	v_writelane_b32 v254, s4, 0
	s_nop 1
	v_writelane_b32 v254, s5, 1
	v_writelane_b32 v254, s6, 2
	v_writelane_b32 v254, s7, 3
	v_writelane_b32 v254, s8, 4
	v_writelane_b32 v254, s9, 5
	v_writelane_b32 v254, s10, 6
	v_writelane_b32 v254, s11, 7
	s_add_u32 s4, s0, 0xa8
	s_addc_u32 s5, s1, 0
	s_and_saveexec_b64 s[6:7], vcc
	v_lshl_add_u32 v1, v211, 2, 0
	v_add_u32_e32 v1, 0x23700, v1
	v_mov_b32_e32 v2, 0
	ds_write_b32 v1, v2
	s_or_b64 exec, exec, s[6:7]
	s_waitcnt lgkmcnt(0)
	s_barrier
	v_writelane_b32 v255, 0, 41
	v_writelane_b32 v255, 0, 42
	s_getreg_b32 s2, hwreg(HW_REG_XCC_ID, 0, 4)
	s_and_b32 s2, s2, 15
	v_cmp_eq_u32_e64 s[8:9], 0, v211
	s_mov_b64 s[6:7], exec
	s_nop 0
	v_writelane_b32 v254, s8, 8
	s_nop 1
	v_writelane_b32 v254, s9, 9
	s_and_b64 s[8:9], s[6:7], s[8:9]
	s_mov_b64 exec, s[8:9]
	s_cbranch_execz .LBB0_5
	s_mov_b64 s[8:9], exec
	v_mbcnt_lo_u32_b32 v1, s8, 0
	v_mbcnt_hi_u32_b32 v1, s9, v1
	v_cmp_eq_u32_e32 vcc, 0, v1
	s_and_b64 s[10:11], exec, vcc
	s_mov_b64 exec, s[10:11]
	s_cbranch_execz .LBB0_5
	s_lshl_b32 s10, s2, 8
	s_bcnt1_i32_b64 s8, s[8:9]
	v_mov_b32_e32 v1, s10
	v_mov_b32_e32 v2, s8
	global_atomic_add v1, v2, s[92:93] offset:1024
	s_and_b32 s10, s74, 7
	s_lshl_b32 s10, s10, 2
	s_add_u32 s10, s10, 0x5000
	v_mov_b32_e32 v1, s10
	s_add_u32 s10, s2, 1
	v_mov_b32_e32 v2, s10
	global_atomic_umax v1, v2, s[92:93]
	s_sub_u32 s10, 16, s2
	v_mov_b32_e32 v3, s10
	global_atomic_umax v1, v3, s[92:93] offset:64

.LBB0_105:
	s_cmpk_gt_i32 s6, 0xff
	s_cbranch_scc1 .LBB0_130
	s_lshl_b32 s2, s1, 2
	s_ashr_i32 s3, s2, 31
	v_readlane_b32 s16, v254, 10
	s_lshl_b64 s[2:3], s[2:3], 2
	v_readlane_b32 s18, v254, 12
	v_readlane_b32 s26, v254, 20
	v_readlane_b32 s19, v254, 13
	v_readlane_b32 s27, v254, 21
	s_add_u32 s18, s26, s2
	v_readlane_b32 s28, v254, 22
	s_addc_u32 s19, s27, s3
	v_readlane_b32 s29, v254, 23
	s_add_u32 s2, s28, s2
	v_and_b32_e32 v0, 63, v138
	s_addc_u32 s3, s29, s3
	s_ashr_i32 s1, s0, 8
	v_lshl_add_u32 v22, v0, 4, 0
	s_lshl_b32 s14, s1, 9
	v_lshlrev_b32_e32 v0, 11, v138
	v_readlane_b32 s20, v254, 14
	v_readlane_b32 s21, v254, 15
	s_ashr_i32 s15, s14, 31
	v_and_b32_e32 v196, 0x3800, v0
	v_readlane_b32 s22, v254, 16
	s_bfe_u32 s4, s0, 0x20006
	v_lshl_add_u64 v[0:1], s[12:13], 0, v[196:197]
	s_lshl_b64 s[20:21], s[14:15], 1
	s_lshl_b32 s22, s4, 4
	v_lshl_add_u64 v[0:1], v[0:1], 0, s[20:21]
	v_and_b32_e32 v196, 48, v138
	v_lshl_add_u64 v[0:1], v[0:1], 0, v[196:197]
	s_mov_b64 s[14:15], 0x800000
	s_cmp_eq_u32 s1, 1
	v_lshl_add_u64 v[8:9], v[0:1], 0, s[14:15]
	s_cselect_b64 s[14:15], -1, 0
	s_lshl_b32 s1, s4, 10
	v_readlane_b32 s17, v254, 11
	s_cmpk_lt_u32 s0, 0x100
	v_lshlrev_b32_e32 v0, 2, v138
	s_cselect_b64 s[16:17], -1, 0
	s_and_b32 s0, s0, 0xc0
	v_and_b32_e32 v0, 12, v0
	v_mov_b32_e32 v1, v197
	s_and_b32 s7, s6, 7
	s_lshl_b32 s7, s7, 5
	s_lshr_b32 s6, s6, 3
	s_or_b32 s6, s6, s7
	s_ashr_i32 s7, s6, 31
	v_bfe_u32 v2, v138, 4, 2
	v_lshl_add_u32 v23, s0, 4, v22
	v_lshl_add_u64 v[12:13], s[2:3], 0, v[0:1]
	s_lshl_b64 s[2:3], s[6:7], 10
	s_lshl_b32 s0, s4, 8
	v_lshl_add_u64 v[10:11], s[18:19], 0, v[0:1]
	s_or_b32 s0, s2, s0
	v_lshlrev_b32_e32 v1, 6, v2
	v_mov_b32_e32 v15, s3
	s_lshl_b64 s[2:3], s[6:7], 6
	v_or3_b32 v14, s0, v1, v0
	s_or_b32 s0, s2, s22
	v_and_b32_e32 v4, 15, v138
	v_lshl_or_b32 v2, v2, 2, s0
	v_mov_b32_e32 v3, s3
	v_lshlrev_b64 v[16:17], 4, v[2:3]
	v_or_b32_e32 v2, s0, v4
	v_or_b32_e32 v16, v16, v0
	v_lshlrev_b64 v[0:1], 11, v[2:3]
	v_or_b32_e32 v0, v0, v196
	s_ashr_i32 s9, s8, 31
	v_lshl_add_u64 v[0:1], v[0:1], 0, s[20:21]
	s_mov_b64 s[2:3], 0xae00200
	v_cmp_gt_u32_e64 s[38:39], 8, v4
	v_cmp_lt_u32_e64 s[40:41], 3, v4
	s_lshl_b64 s[18:19], s[8:9], 10
	v_lshl_add_u64 v[18:19], v[0:1], 0, s[2:3]
	s_lshl_b64 s[42:43], s[8:9], 17
	v_readlane_b32 s23, v254, 17
	v_readlane_b32 s24, v254, 18
	v_readlane_b32 s25, v254, 19
	v_readlane_b32 s30, v254, 24
	v_readlane_b32 s31, v254, 25
	s_branch .LBB0_110

.LBB0_130:
	s_waitcnt vmcnt(0)
	s_waitcnt vmcnt(0) lgkmcnt(0)
	s_barrier
	s_mov_b64 s[6:7], exec
	v_readlane_b32 s0, v254, 8
	v_readlane_b32 s1, v254, 9
	s_and_b64 s[0:1], s[6:7], s[0:1]
	s_mov_b64 exec, s[0:1]
	s_cbranch_execz .LBB0_182
	v_readlane_b32 s0, v255, 31
	s_cmp_lg_u32 s0, 0
	s_cbranch_scc1 .Lcls_chk_done
	s_and_b32 s0, s74, 7
	s_lshl_b32 s0, s0, 2
	v_mov_b32_e32 v2, s0
	s_add_u32 s2, s92, 0x5000
	s_addc_u32 s3, s93, 0
	global_load_dword v0, v2, s[2:3] sc1
	global_load_dword v1, v2, s[2:3] offset:64 sc1
	s_waitcnt vmcnt(0)
	v_add_u32_e32 v0, v0, v1
	s_nop 0
	v_readfirstlane_b32 s0, v0
	s_cmp_eq_u32 s0, 17
	s_cselect_b32 s1, 1, 0
	v_writelane_b32 v255, s1, 42
	s_cbranch_scc1 .Lcls_chk_done
	v_mov_b32_e32 v0, 1
	global_atomic_add v197, v0, s[2:3] offset:128
	s_waitcnt vmcnt(0)

.LBB0_162:
	s_andn2_saveexec_b64 s[0:1], s[8:9]
	s_cbranch_execz .LBB0_182
	s_mov_b64 s[8:9], exec
	v_readlane_b32 s2, v255, 42
	s_cmp_eq_u32 s2, 1
	s_cbranch_scc1 .Lb2_nowb
	buffer_wbl2 sc1
.Lb2_nowb:
	s_waitcnt lgkmcnt(0)
	s_waitcnt vmcnt(0)
	v_mbcnt_lo_u32_b32 v1, s8, 0
	v_mbcnt_hi_u32_b32 v1, s9, v1
	v_cmp_eq_u32_e32 vcc, 0, v1
	s_and_saveexec_b64 s[12:13], vcc
	s_cbranch_execz .LBB0_165
	s_bcnt1_i32_b64 s0, s[8:9]
	v_mov_b32_e32 v2, s0
	v_readlane_b32 s0, v255, 18
	v_readlane_b32 s1, v255, 19
	s_nop 4
	global_atomic_add v2, v197, v2, s[0:1] sc0
